# baseline (speedup 1.0000x reference)
; #define LAS __attribute__((address_space(3)))
; __device__ __forceinline__ void attn_phase(LAS unsigned char* lds, bf16_t* Qb, const bf16_t* KVb, const bf16_t* GZ, const float* sinkp) {
;     ...
;                     float mx = __builtin_fmaxf(s0[0], s1[0]);
; #pragma unroll
;                     for (int r = 1; r < 16; ++r) { float t_; asm("v_max3_f32 %0, %1, %2, %3" : "=v"(t_) : "v"(mx), "v"(s0[r]), "v"(s1[r])); mx = t_; }
;                     mx = fmaxf(mx, __shfl_xor(mx, 32));
;                     const float mx2 = mx * SC;
;                     const bool bump = mx2 > m_run + 8.f;
;                     if (__any(bump)) {
;     ...
;                         s16x4 va[2][4][2];
; #pragma unroll
;                         for (int dt = 0; dt < 4; ++dt) { va[0][dt][0] = __builtin_amdgcn_ds_read_tr16_b64_v4i16((LAS s16x4*)(Vc + vaddr[dt][0])); va[0][dt][1] = __builtin_amdgcn_ds_read_tr16_b64_v4i16((LAS s16x4*)(Vc + vaddr[dt][1])); }
;                         __builtin_amdgcn_sched_barrier(0);
; #pragma unroll
;                         for (int c = 0; c < 4; ++c) {
;                             if (c < 3) {
; #pragma unroll
;                                 for (int dt = 0; dt < 4; ++dt) { va[(c + 1) & 1][dt][0] = __builtin_amdgcn_ds_read_tr16_b64_v4i16((LAS s16x4*)(Vc + vaddr[dt][0] + (c + 1) * 4096)); va[(c + 1) & 1][dt][1] = __builtin_amdgcn_ds_read_tr16_b64_v4i16((LAS s16x4*)(Vc + vaddr[dt][1] + (c + 1) * 4096)); }
.LBB0_176:
	v_add_u32_e32 v220, s3, v161
	v_add_u32_e32 v221, s3, v162
	v_add_u32_e32 v202, s3, v163
	v_add_u32_e32 v203, s3, v164
	v_add_u32_e32 v204, s3, v165
	v_add_u32_e32 v205, s3, v166
	v_add_u32_e32 v206, s3, v167
	v_add_u32_e32 v207, s3, v168
	ds_read_b64_tr_b16 v[208:209], v220 offset:16384
	ds_read_b64_tr_b16 v[210:211], v221 offset:16384
	ds_read_b64_tr_b16 v[212:213], v202 offset:16384
	ds_read_b64_tr_b16 v[214:215], v203 offset:16384
	ds_read_b64_tr_b16 v[216:217], v204 offset:16384
	ds_read_b64_tr_b16 v[218:219], v205 offset:16384
	ds_read_b64_tr_b16 v[228:229], v206 offset:16384
	ds_read_b64_tr_b16 v[230:231], v207 offset:16384
	ds_read_b64_tr_b16 v[238:239], v220 offset:20480
	ds_read_b64_tr_b16 v[240:241], v221 offset:20480
	ds_read_b64_tr_b16 v[242:243], v202 offset:20480
	ds_read_b64_tr_b16 v[244:245], v203 offset:20480
	ds_read_b64_tr_b16 v[246:247], v204 offset:20480
	ds_read_b64_tr_b16 v[248:249], v205 offset:20480
	ds_read_b64_tr_b16 v[250:251], v206 offset:20480
	ds_read_b64_tr_b16 v[252:253], v207 offset:20480
	v_max_f32_e32 v177, v64, v64
	v_max_f32_e32 v178, v80, v80
	v_max_f32_e32 v177, v178, v177
	v_max_f32_e32 v178, v81, v65
	v_max3_f32 v177, v177, v82, v66
	v_max3_f32 v178, v178, v83, v67
	v_max3_f32 v177, v177, v84, v68
	v_max3_f32 v178, v178, v85, v69
	v_max3_f32 v177, v177, v86, v70
	v_max3_f32 v178, v178, v87, v71
	v_max3_f32 v177, v177, v88, v72
	v_max3_f32 v178, v178, v89, v73
	v_max3_f32 v177, v177, v90, v74
	v_max3_f32 v178, v178, v91, v75
	v_max3_f32 v177, v177, v92, v76
	v_max3_f32 v178, v178, v93, v77
	v_max3_f32 v177, v177, v94, v78
	v_max3_f32 v178, v178, v95, v79
	v_max_f32_e32 v177, v177, v178
	v_max_f32_e32 v177, v177, v177
	v_mov_b32_e32 v178, v177
	s_nop 1
	v_permlane32_swap_b32_e32 v178, v177
	v_max_f32_e32 v177, v177, v178
	v_mul_f32_e32 v177, 0x3e0293ee, v177
	v_add_f32_e32 v178, 0x41000000, v176
	v_cmp_gt_f32_e32 vcc, v177, v178
	s_cbranch_vccnz .Lattn_bump

; __device__ __forceinline__ void attn_phase(LAS unsigned char* lds, bf16_t* Qb, const bf16_t* KVb, const bf16_t* GZ, const float* sinkp) {
;     ...
;                     if (__any(bump)) {
;                         const float m_new = bump ? mx2 : m_run, alpha = __builtin_amdgcn_exp2f(m_run - m_new);
;                         m_run = m_new; l_run *= alpha;
; #pragma unroll
;                         for (int dt = 0; dt < 4; ++dt)
; #pragma unroll
;                             for (int r = 0; r < 16; ++r) o[dt][r] *= alpha;
;                     }
.Lattn_bump:
	s_nop 0
	v_cndmask_b32_e32 v177, v176, v177, vcc
	v_sub_f32_e32 v176, v176, v177
	v_exp_f32_e32 v176, v176
	s_nop 0
	v_pk_mul_f32 v[62:63], v[62:63], v[176:177] op_sel_hi:[1,0]
	v_pk_mul_f32 v[60:61], v[60:61], v[176:177] op_sel_hi:[1,0]
	v_pk_mul_f32 v[58:59], v[58:59], v[176:177] op_sel_hi:[1,0]
	v_pk_mul_f32 v[56:57], v[56:57], v[176:177] op_sel_hi:[1,0]
	v_pk_mul_f32 v[54:55], v[54:55], v[176:177] op_sel_hi:[1,0]
	v_pk_mul_f32 v[52:53], v[52:53], v[176:177] op_sel_hi:[1,0]
	v_pk_mul_f32 v[50:51], v[50:51], v[176:177] op_sel_hi:[1,0]
	v_pk_mul_f32 v[48:49], v[48:49], v[176:177] op_sel_hi:[1,0]
	v_pk_mul_f32 v[46:47], v[46:47], v[176:177] op_sel_hi:[1,0]
	v_pk_mul_f32 v[44:45], v[44:45], v[176:177] op_sel_hi:[1,0]
	v_pk_mul_f32 v[42:43], v[42:43], v[176:177] op_sel_hi:[1,0]
	v_pk_mul_f32 v[40:41], v[40:41], v[176:177] op_sel_hi:[1,0]
	v_pk_mul_f32 v[38:39], v[38:39], v[176:177] op_sel_hi:[1,0]
	v_pk_mul_f32 v[36:37], v[36:37], v[176:177] op_sel_hi:[1,0]
	v_pk_mul_f32 v[34:35], v[34:35], v[176:177] op_sel_hi:[1,0]
	v_pk_mul_f32 v[32:33], v[32:33], v[176:177] op_sel_hi:[1,0]
	v_pk_mul_f32 v[30:31], v[30:31], v[176:177] op_sel_hi:[1,0]
	v_pk_mul_f32 v[28:29], v[28:29], v[176:177] op_sel_hi:[1,0]
	v_pk_mul_f32 v[26:27], v[26:27], v[176:177] op_sel_hi:[1,0]
	v_pk_mul_f32 v[24:25], v[24:25], v[176:177] op_sel_hi:[1,0]
	v_pk_mul_f32 v[22:23], v[22:23], v[176:177] op_sel_hi:[1,0]
	v_pk_mul_f32 v[20:21], v[20:21], v[176:177] op_sel_hi:[1,0]
	v_pk_mul_f32 v[18:19], v[18:19], v[176:177] op_sel_hi:[1,0]
	v_pk_mul_f32 v[16:17], v[16:17], v[176:177] op_sel_hi:[1,0]
	v_pk_mul_f32 v[14:15], v[14:15], v[176:177] op_sel_hi:[1,0]
	v_pk_mul_f32 v[12:13], v[12:13], v[176:177] op_sel_hi:[1,0]
	v_pk_mul_f32 v[10:11], v[10:11], v[176:177] op_sel_hi:[1,0]
	v_pk_mul_f32 v[8:9], v[8:9], v[176:177] op_sel_hi:[1,0]
	v_pk_mul_f32 v[6:7], v[6:7], v[176:177] op_sel_hi:[1,0]
	v_pk_mul_f32 v[4:5], v[4:5], v[176:177] op_sel_hi:[1,0]
	v_pk_mul_f32 v[2:3], v[2:3], v[176:177] op_sel_hi:[1,0]
	v_pk_mul_f32 v[0:1], v[0:1], v[176:177] op_sel_hi:[1,0]
	v_mul_f32_e32 v173, v173, v176
	v_mov_b32_e32 v176, v177
	s_branch .LBB0_178
